# diff attention QK^T stream now carries the next-K global loads, half of the K fragment reads and the V-tile LDS stores (barrier 1 preceded by a full LDS drain); MLA next-V loads moved to the tail of Q
# speedup vs baseline: 1.0150x; 1.0116x over previous
; DI void diff_item(const Params& p, const GroupP& g, int l_layer, int item, char* smem, bool dry) {
;     ...
;     const bool more = kt + 1 < nkt;
;     if (more) loadK(kt + 1);
;     __builtin_amdgcn_sched_barrier(0);
;     const int key0 = kt * 64;
;     const int relmin = key0 - (qw0 + 31), relmax = key0 + 63 - qw0;
;     const bool farp = relmin >= 128, farn = relmax <= -128;
;     const float binit = (farp ? bpos : (farn ? bneg : 0.f)) - m;
;     f32x16 sa[2];
; #pragma unroll
;     for (int i = 0; i < 16; ++i) { sa[0][i] = binit; sa[1][i] = binit; }
;     {
;       const char* krd = sK + lr * 272 + map * 128 + lh * 16;
;       bf16x8 kf[4][2];
; #pragma unroll
;       for (int ks = 0; ks < 4; ++ks) {
;         kf[ks][0] = *(const bf16x8*)(krd + ks * 32);
;         kf[ks][1] = *(const bf16x8*)(krd + 32 * 272 + ks * 32);
.LBB0_124:
	s_add_i32 s10, s4, s5
	ds_read_b128 v[172:175], v159
	ds_read_b128 v[176:179], v159 offset:8704
	ds_read_b128 v[180:183], v159 offset:32
	ds_read_b128 v[188:191], v159 offset:8736
	s_add_i32 s8, s10, 33
	s_add_i32 s9, s10, 0x7f
	s_cmpk_gt_i32 s8, 0x7f
	s_cselect_b64 vcc, -1, 0
	s_cmpk_lt_i32 s9, 0xff81
	s_cselect_b64 s[8:9], -1, 0
	v_cndmask_b32_e64 v64, 0, v157, s[8:9]
	v_cndmask_b32_e32 v64, v64, v158, vcc
	v_sub_f32_e32 v64, v64, v166
	v_mov_b32_e32 v65, v64
	v_mov_b32_e32 v66, v64
	v_mov_b32_e32 v67, v64
	v_mov_b32_e32 v68, v64
	v_mov_b32_e32 v69, v64
	v_mov_b32_e32 v70, v64
	v_mov_b32_e32 v71, v64
	v_mov_b32_e32 v72, v64
	v_mov_b32_e32 v73, v64
	v_mov_b32_e32 v74, v64
	v_mov_b32_e32 v75, v64
	v_mov_b32_e32 v76, v64
	v_mov_b32_e32 v77, v64
	v_mov_b32_e32 v78, v64
	v_mov_b32_e32 v79, v64
	s_addk_i32 s10, 0xffa1
	s_waitcnt lgkmcnt(3)
	v_mfma_f32_32x32x16_bf16 v[80:95], v[172:175], v[96:99], v[64:79]
	s_waitcnt lgkmcnt(2)
	v_mfma_f32_32x32x16_bf16 v[64:79], v[176:179], v[96:99], v[64:79]
	s_add_i32 s100, s42, 2
	s_cmp_ge_i32 s100, s85
	s_cbranch_scc1 .Ldqk0_nokld
	s_mov_b64 s[100:101], 0x4000
	global_load_dwordx4 v[116:119], v[152:153], off
	v_lshl_add_u64 v[112:113], v[152:153], 0, s[100:101]
	v_lshl_add_u64 v[136:137], v[112:113], 0, s[100:101]
	v_lshl_add_u64 v[140:141], v[136:137], 0, s[100:101]
	global_load_dwordx4 v[112:115], v[112:113], off
	global_load_dwordx4 v[136:139], v[136:137], off
	global_load_dwordx4 v[140:143], v[140:141], off
; #define MFMA(a, b, c) __builtin_amdgcn_mfma_f32_32x32x16_bf16((a), (b), (c), 0, 0, 0)
; DI int crow(int i, int h) { return (i & 3) + 8 * (i >> 2) + 4 * h; }
; DI void diff_item(const Params& p, const GroupP& g, int l_layer, int item, char* smem, bool dry) {
;     ...
;       for (int ks = 0; ks < 4; ++ks) {
;         kf[ks][0] = *(const bf16x8*)(krd + ks * 32);
;         kf[ks][1] = *(const bf16x8*)(krd + 32 * 272 + ks * 32);
;       }
; #pragma unroll
;       for (int ks = 0; ks < 4; ++ks) {
;         sa[0] = MFMA(kf[ks][0], qf[ks], sa[0]);
;         sa[1] = MFMA(kf[ks][1], qf[ks], sa[1]);
;       }
;     }
;     if (!farp && !farn) {
;       asm volatile("; near-diagonal bias tile" ::: "memory");
; #pragma unroll
;       for (int kb = 0; kb < 2; ++kb)
; #pragma unroll
;         for (int i = 0; i < 16; ++i) {
;           int rel = key0 + kb * 32 + crow(i, lh) - qpos;
;           rel = rel < -128 ? -128 : (rel > 128 ? 128 : rel);
;           sa[kb][i] += sBias[rel + 128];
;         }
;     }
.Ldqk0_nokld:
	ds_read_b128 v[192:195], v159 offset:64
	ds_read_b128 v[196:199], v159 offset:8768
	s_waitcnt lgkmcnt(3)
	v_mfma_f32_32x32x16_bf16 v[80:95], v[180:183], v[100:103], v[80:95]
	ds_write2_b64 v167, v[120:121], v[122:123] offset0:128 offset1:130
	ds_read_b128 v[202:205], v159 offset:96
	s_waitcnt lgkmcnt(4)
	v_mfma_f32_32x32x16_bf16 v[64:79], v[188:191], v[100:103], v[64:79]
	ds_write2_b64 v168, v[124:125], v[126:127] offset0:192 offset1:194
	ds_read_b128 v[206:209], v159 offset:8800
	s_waitcnt lgkmcnt(5)
	v_mfma_f32_32x32x16_bf16 v[80:95], v[192:195], v[104:107], v[80:95]
	ds_write2_b64 v169, v[128:129], v[130:131] offset1:2
	s_waitcnt lgkmcnt(5)
	v_mfma_f32_32x32x16_bf16 v[64:79], v[196:199], v[104:107], v[64:79]
	ds_write2_b64 v170, v[132:133], v[134:135] offset0:64 offset1:66
	s_waitcnt lgkmcnt(4)
	v_mfma_f32_32x32x16_bf16 v[80:95], v[202:205], v[108:111], v[80:95]
	s_waitcnt lgkmcnt(0)
	v_mfma_f32_32x32x16_bf16 v[64:79], v[206:209], v[108:111], v[64:79]
	s_cmp_lt_u32 s10, 0xfffffea3
	s_cbranch_scc1 .LBB0_126
	v_add_u32_e32 v184, s5, v171
	v_add_u32_e32 v172, 64, v184
	v_med3_i32 v172, v172, s84, v213
	v_lshlrev_b32_e32 v180, 2, v172
	v_add_u32_e32 v172, 0x41, v184
	v_med3_i32 v172, v172, s84, v213
	v_lshlrev_b32_e32 v181, 2, v172
	v_add_u32_e32 v172, 0x42, v184
	v_med3_i32 v172, v172, s84, v213
	v_lshlrev_b32_e32 v182, 2, v172
	v_add_u32_e32 v172, 0x43, v184
	v_med3_i32 v172, v172, s84, v213
	v_lshlrev_b32_e32 v183, 2, v172
	v_add_u32_e32 v172, 0x48, v184
	v_med3_i32 v172, v172, s84, v213
	v_lshlrev_b32_e32 v188, 2, v172
	v_add_u32_e32 v172, 0x49, v184
	v_med3_i32 v172, v172, s84, v213
	v_lshlrev_b32_e32 v189, 2, v172
	v_add_u32_e32 v172, 0x4a, v184
	v_med3_i32 v172, v172, s84, v213
	v_lshlrev_b32_e32 v190, 2, v172
	v_add_u32_e32 v172, 0x4b, v184
	v_med3_i32 v172, v172, s84, v213
	v_lshlrev_b32_e32 v191, 2, v172
	v_add_u32_e32 v172, 0x50, v184
	v_add_u32_e32 v173, 0x51, v184
	v_add_u32_e32 v174, 0x52, v184
	v_add_u32_e32 v175, 0x53, v184
	v_add_u32_e32 v176, 0x58, v184
	v_add_u32_e32 v177, 0x59, v184
	v_add_u32_e32 v178, 0x5a, v184
	v_add_u32_e32 v179, 0x5b, v184
	v_med3_i32 v172, v172, s84, v213
	v_med3_i32 v173, v173, s84, v213
	v_med3_i32 v174, v174, s84, v213
	v_med3_i32 v175, v175, s84, v213
	v_med3_i32 v176, v176, s84, v213
	v_med3_i32 v177, v177, s84, v213
	v_med3_i32 v178, v178, s84, v213
	v_med3_i32 v179, v179, s84, v213
	v_lshlrev_b32_e32 v172, 2, v172
	v_lshlrev_b32_e32 v173, 2, v173
	v_lshlrev_b32_e32 v174, 2, v174
	v_lshlrev_b32_e32 v175, 2, v175
	v_lshlrev_b32_e32 v176, 2, v176
	v_lshlrev_b32_e32 v177, 2, v177
	v_lshlrev_b32_e32 v178, 2, v178
	v_lshlrev_b32_e32 v179, 2, v179
	ds_read_b32 v172, v172 offset:36352
	ds_read_b32 v173, v173 offset:36352
	ds_read_b32 v174, v174 offset:36352
	ds_read_b32 v175, v175 offset:36352
	ds_read_b32 v176, v176 offset:36352
	ds_read_b32 v177, v177 offset:36352
	ds_read_b32 v178, v178 offset:36352
	ds_read_b32 v179, v179 offset:36352
	ds_read_b32 v180, v180 offset:36352
	ds_read_b32 v181, v181 offset:36352
	ds_read_b32 v182, v182 offset:36352
	ds_read_b32 v183, v183 offset:36352
	ds_read_b32 v188, v188 offset:36352
	ds_read_b32 v189, v189 offset:36352
	ds_read_b32 v190, v190 offset:36352
	ds_read_b32 v191, v191 offset:36352
	s_waitcnt lgkmcnt(14)
	v_pk_add_f32 v[88:89], v[88:89], v[172:173]
	v_add_u32_e32 v172, 0x60, v184
	v_med3_i32 v172, v172, s84, v213
	s_waitcnt lgkmcnt(6)
	v_pk_add_f32 v[80:81], v[80:81], v[180:181]
	v_lshlrev_b32_e32 v180, 2, v172
	v_add_u32_e32 v172, 0x61, v184
	v_med3_i32 v172, v172, s84, v213
	v_lshlrev_b32_e32 v181, 2, v172
	v_add_u32_e32 v172, 0x62, v184
	v_med3_i32 v172, v172, s84, v213
	s_waitcnt lgkmcnt(4)
	v_pk_add_f32 v[82:83], v[82:83], v[182:183]
	v_lshlrev_b32_e32 v182, 2, v172
	v_add_u32_e32 v172, 0x63, v184
	v_med3_i32 v172, v172, s84, v213
	v_lshlrev_b32_e32 v183, 2, v172
	v_add_u32_e32 v172, 0x68, v184
	v_med3_i32 v172, v172, s84, v213
	s_waitcnt lgkmcnt(2)
	v_pk_add_f32 v[84:85], v[84:85], v[188:189]
	v_lshlrev_b32_e32 v188, 2, v172
	v_add_u32_e32 v172, 0x69, v184
	v_med3_i32 v172, v172, s84, v213
	v_lshlrev_b32_e32 v189, 2, v172
	v_add_u32_e32 v172, 0x6a, v184
	v_med3_i32 v172, v172, s84, v213
	s_waitcnt lgkmcnt(0)
	v_pk_add_f32 v[86:87], v[86:87], v[190:191]
	v_lshlrev_b32_e32 v190, 2, v172
	v_add_u32_e32 v172, 0x6b, v184
	v_med3_i32 v172, v172, s84, v213
	v_pk_add_f32 v[94:95], v[94:95], v[178:179]
	v_pk_add_f32 v[92:93], v[92:93], v[176:177]
	v_pk_add_f32 v[90:91], v[90:91], v[174:175]
	v_lshlrev_b32_e32 v191, 2, v172
	v_add_u32_e32 v172, 0x70, v184
	v_add_u32_e32 v173, 0x71, v184
	v_add_u32_e32 v174, 0x72, v184
	v_add_u32_e32 v175, 0x73, v184
	v_add_u32_e32 v176, 0x78, v184
	v_add_u32_e32 v177, 0x79, v184
	v_add_u32_e32 v178, 0x7a, v184
	v_add_u32_e32 v179, 0x7b, v184
	v_med3_i32 v172, v172, s84, v213
	v_med3_i32 v173, v173, s84, v213
	v_med3_i32 v174, v174, s84, v213
	v_med3_i32 v175, v175, s84, v213
	v_med3_i32 v176, v176, s84, v213
	v_med3_i32 v177, v177, s84, v213
	v_med3_i32 v178, v178, s84, v213
	v_med3_i32 v179, v179, s84, v213
	v_lshlrev_b32_e32 v172, 2, v172
	v_lshlrev_b32_e32 v173, 2, v173
	v_lshlrev_b32_e32 v174, 2, v174
	v_lshlrev_b32_e32 v175, 2, v175
	v_lshlrev_b32_e32 v176, 2, v176
	v_lshlrev_b32_e32 v177, 2, v177
	v_lshlrev_b32_e32 v178, 2, v178
	v_lshlrev_b32_e32 v179, 2, v179
	ds_read_b32 v172, v172 offset:36352
	ds_read_b32 v173, v173 offset:36352
	ds_read_b32 v174, v174 offset:36352
	ds_read_b32 v175, v175 offset:36352
	ds_read_b32 v176, v176 offset:36352
	ds_read_b32 v177, v177 offset:36352
	ds_read_b32 v178, v178 offset:36352
	ds_read_b32 v179, v179 offset:36352
	ds_read_b32 v180, v180 offset:36352
	ds_read_b32 v181, v181 offset:36352
	ds_read_b32 v182, v182 offset:36352
	ds_read_b32 v183, v183 offset:36352
	ds_read_b32 v188, v188 offset:36352
	ds_read_b32 v189, v189 offset:36352
	ds_read_b32 v190, v190 offset:36352
	ds_read_b32 v191, v191 offset:36352
	s_waitcnt lgkmcnt(8)
	v_pk_add_f32 v[78:79], v[78:79], v[178:179]
	v_pk_add_f32 v[76:77], v[76:77], v[176:177]
	v_pk_add_f32 v[74:75], v[74:75], v[174:175]
	v_pk_add_f32 v[72:73], v[72:73], v[172:173]
	s_waitcnt lgkmcnt(0)
	v_pk_add_f32 v[70:71], v[70:71], v[190:191]
	v_pk_add_f32 v[68:69], v[68:69], v[188:189]
	v_pk_add_f32 v[66:67], v[66:67], v[182:183]
	v_pk_add_f32 v[64:65], v[64:65], v[180:181]

; #define MFMA(a, b, c) __builtin_amdgcn_mfma_f32_32x32x16_bf16((a), (b), (c), 0, 0, 0)
; DI int crow(int i, int h) { return (i & 3) + 8 * (i >> 2) + 4 * h; }
; DI void load_vtile(u32x4 (&rv)[4], const u16* __restrict__ vbase, int Lp, int key0, unsigned voffV) {
;   const char* ub = (const char*)vbase + (long)key0 * 2;
; #pragma unroll
;   for (int i = 0; i < 4; ++i) rv[i] = *(const u32x4*)(ub + (long)(32 * i) * Lp * 2 + voffV);
; }
; DI void mla_item(const Params& p, const GroupP& g, int item, char* smem, bool dry) {
;     ...
;       for (int ks = 0; ks < 12; ++ks) {
;         if (ks + 2 < 12) {
;           kf[(ks + 2) % 3][0] = *(const bf16x8*)(krd + (ks + 2) * 32);
;           kf[(ks + 2) % 3][1] = *(const bf16x8*)(krd + 32 * 400 + (ks + 2) * 32);
;           __builtin_amdgcn_sched_group_barrier(0x100, 2, 0);
;         }
;         sa[0] = MFMA(kf[ks % 3][0], qf[ks], sa[0]);
;         sa[1] = MFMA(kf[ks % 3][1], qf[ks], sa[1]);
;         __builtin_amdgcn_sched_group_barrier(0x008, 2, 0);
;       }
;     }
;     if (kt == nkt - 1) {
;       asm volatile("; masked tail tile" ::: "memory");
; #pragma unroll
;       for (int kb = 0; kb < 2; ++kb)
; #pragma unroll
;         for (int i = 0; i < 16; ++i)
;           if (kt * 64 + kb * 32 + crow(i, lh) >= L) sa[kb][i] = -1e30f;
;     }
;     __syncthreads();
;     if (more) { storeK(); load_vtile(rv, vbase, Lp, (kt + 1) * 64, voffV); }
.Lqk0_nokld:
	s_waitcnt lgkmcnt(5)
	v_mfma_f32_32x32x16_bf16 v[80:95], v[232:235], v[100:103], v[80:95]
	s_waitcnt lgkmcnt(4)
	v_mfma_f32_32x32x16_bf16 v[64:79], v[236:239], v[100:103], v[64:79]
	ds_read_b128 v[232:235], v184 offset:128
	ds_read_b128 v[236:239], v184 offset:12928
	s_waitcnt lgkmcnt(5)
	v_mfma_f32_32x32x16_bf16 v[80:95], v[240:243], v[104:107], v[80:95]
	s_waitcnt lgkmcnt(4)
	v_mfma_f32_32x32x16_bf16 v[64:79], v[244:247], v[104:107], v[64:79]
	ds_read_b128 v[240:243], v184 offset:160
	ds_read_b128 v[244:247], v184 offset:12960
	s_waitcnt lgkmcnt(5)
	v_mfma_f32_32x32x16_bf16 v[80:95], v[202:205], v[108:111], v[80:95]
	s_waitcnt lgkmcnt(4)
	v_mfma_f32_32x32x16_bf16 v[64:79], v[206:209], v[108:111], v[64:79]
	ds_read_b128 v[202:205], v184 offset:192
	ds_read_b128 v[206:209], v184 offset:12992
	ds_write2_b64 v227, v[152:153], v[154:155] offset0:128 offset1:130
	s_waitcnt lgkmcnt(6)
	v_mfma_f32_32x32x16_bf16 v[80:95], v[232:235], v[112:115], v[80:95]
	s_waitcnt lgkmcnt(5)
	v_mfma_f32_32x32x16_bf16 v[64:79], v[236:239], v[112:115], v[64:79]
	ds_read_b128 v[232:235], v184 offset:224
	ds_read_b128 v[236:239], v184 offset:13024
	ds_write2_b64 v228, v[156:157], v[158:159] offset0:192 offset1:194
	s_waitcnt lgkmcnt(7)
	v_mfma_f32_32x32x16_bf16 v[80:95], v[240:243], v[116:119], v[80:95]
	s_waitcnt lgkmcnt(6)
	v_mfma_f32_32x32x16_bf16 v[64:79], v[244:247], v[116:119], v[64:79]
	ds_read_b128 v[240:243], v184 offset:256
	ds_read_b128 v[244:247], v184 offset:13056
	ds_write2_b64 v229, v[164:165], v[166:167] offset1:2
	s_waitcnt lgkmcnt(8)
	v_mfma_f32_32x32x16_bf16 v[80:95], v[202:205], v[120:123], v[80:95]
	s_waitcnt lgkmcnt(7)
	v_mfma_f32_32x32x16_bf16 v[64:79], v[206:209], v[120:123], v[64:79]
	ds_read_b128 v[202:205], v184 offset:288
	ds_read_b128 v[206:209], v184 offset:13088
	ds_write2_b64 v230, v[168:169], v[170:171] offset0:64 offset1:66
	s_cmp_ge_i32 s92, s85
	s_cbranch_scc1 .Lpvm0_novl
	v_lshl_add_u64 v[152:153], v[194:195], 0, s[94:95]
	v_lshl_add_u64 v[156:157], v[152:153], 0, s[88:89]
	v_lshl_add_u64 v[164:165], v[156:157], 0, s[88:89]
	v_lshl_add_u64 v[168:169], v[164:165], 0, s[88:89]
	global_load_dwordx4 v[152:155], v[152:153], off
	global_load_dwordx4 v[156:159], v[156:157], off
	global_load_dwordx4 v[164:167], v[164:165], off
	global_load_dwordx4 v[168:171], v[168:169], off
.Lpvm0_novl:
	s_waitcnt lgkmcnt(8)
	v_mfma_f32_32x32x16_bf16 v[80:95], v[232:235], v[124:127], v[80:95]
	s_waitcnt lgkmcnt(7)
	v_mfma_f32_32x32x16_bf16 v[64:79], v[236:239], v[124:127], v[64:79]
	ds_read_b128 v[232:235], v184 offset:320
	ds_read_b128 v[236:239], v184 offset:13120
	s_waitcnt lgkmcnt(7)
	v_mfma_f32_32x32x16_bf16 v[80:95], v[240:243], v[128:131], v[80:95]
	s_waitcnt lgkmcnt(6)
	v_mfma_f32_32x32x16_bf16 v[64:79], v[244:247], v[128:131], v[64:79]
	ds_read_b128 v[240:243], v184 offset:352
	ds_read_b128 v[244:247], v184 offset:13152
	s_waitcnt lgkmcnt(6)
	v_mfma_f32_32x32x16_bf16 v[80:95], v[202:205], v[132:135], v[80:95]
	s_waitcnt lgkmcnt(5)
	v_mfma_f32_32x32x16_bf16 v[64:79], v[206:209], v[132:135], v[64:79]
	s_waitcnt lgkmcnt(3)
	v_mfma_f32_32x32x16_bf16 v[80:95], v[232:235], v[136:139], v[80:95]
	s_waitcnt lgkmcnt(2)
	v_mfma_f32_32x32x16_bf16 v[64:79], v[236:239], v[136:139], v[64:79]
	s_waitcnt lgkmcnt(1)
	v_mfma_f32_32x32x16_bf16 v[80:95], v[240:243], v[140:143], v[80:95]
	s_waitcnt lgkmcnt(0)
	v_mfma_f32_32x32x16_bf16 v[64:79], v[244:247], v[140:143], v[64:79]
	s_cmp_lg_u32 s85, s92
	s_cbranch_scc1 .LBB0_156
	s_nop 8
	v_cndmask_b32_e64 v95, v214, v95, s[8:9]
	v_cndmask_b32_e64 v94, v214, v94, s[12:13]
	v_cndmask_b32_e64 v93, v214, v93, s[14:15]
	v_cndmask_b32_e64 v92, v214, v92, s[16:17]
	v_cndmask_b32_e64 v91, v214, v91, s[18:19]
	v_cndmask_b32_e64 v90, v214, v90, s[20:21]
	v_cndmask_b32_e64 v89, v214, v89, s[22:23]
	v_cndmask_b32_e64 v88, v214, v88, s[24:25]
	v_cndmask_b32_e64 v87, v214, v87, s[26:27]
	v_cndmask_b32_e64 v86, v214, v86, s[28:29]
	v_cndmask_b32_e64 v85, v214, v85, s[30:31]
	v_cndmask_b32_e64 v84, v214, v84, s[34:35]
	v_cndmask_b32_e64 v83, v214, v83, s[36:37]
	v_cndmask_b32_e64 v82, v214, v82, s[38:39]
	v_cndmask_b32_e64 v81, v214, v81, s[40:41]
	v_cndmask_b32_e64 v80, v214, v80, s[42:43]
	v_cndmask_b32_e64 v79, v214, v79, s[10:11]
	v_cndmask_b32_e64 v78, v214, v78, s[44:45]
	v_cndmask_b32_e64 v77, v214, v77, s[46:47]
	v_cndmask_b32_e64 v76, v214, v76, s[48:49]
	v_cndmask_b32_e64 v75, v214, v75, s[50:51]
	v_cndmask_b32_e64 v74, v214, v74, s[52:53]
	v_cndmask_b32_e64 v73, v214, v73, s[54:55]
	v_cndmask_b32_e64 v72, v214, v72, s[56:57]
	v_cndmask_b32_e64 v71, v214, v71, s[58:59]
	v_cndmask_b32_e64 v70, v214, v70, s[60:61]
	v_cndmask_b32_e64 v69, v214, v69, s[62:63]
	v_cndmask_b32_e64 v68, v214, v68, s[64:65]
	v_cndmask_b32_e64 v67, v214, v67, s[66:67]
	v_cndmask_b32_e64 v66, v214, v66, s[68:69]
	v_cndmask_b32_e64 v65, v214, v65, s[70:71]
	v_cndmask_b32_e64 v64, v214, v64, s[72:73]

; DI void diff_item(const Params& p, const GroupP& g, int l_layer, int item, char* smem, bool dry) {
;     ...
;     const bool more = kt + 1 < nkt;
;     if (more) loadK(kt + 1);
;     __builtin_amdgcn_sched_barrier(0);
;     const int key0 = kt * 64;
;     const int relmin = key0 - (qw0 + 31), relmax = key0 + 63 - qw0;
;     const bool farp = relmin >= 128, farn = relmax <= -128;
;     const float binit = (farp ? bpos : (farn ? bneg : 0.f)) - m;
;     f32x16 sa[2];
; #pragma unroll
;     for (int i = 0; i < 16; ++i) { sa[0][i] = binit; sa[1][i] = binit; }
;     {
;       const char* krd = sK + lr * 272 + map * 128 + lh * 16;
;       bf16x8 kf[4][2];
; #pragma unroll
;       for (int ks = 0; ks < 4; ++ks) {
;         kf[ks][0] = *(const bf16x8*)(krd + ks * 32);
;         kf[ks][1] = *(const bf16x8*)(krd + 32 * 272 + ks * 32);
.LBB0_196:
	s_add_i32 s10, s4, s5
	ds_read_b128 v[172:175], v159
	ds_read_b128 v[176:179], v159 offset:8704
	ds_read_b128 v[180:183], v159 offset:32
	ds_read_b128 v[188:191], v159 offset:8736
	s_add_i32 s8, s10, 33
	s_add_i32 s9, s10, 0x7f
	s_cmpk_gt_i32 s8, 0x7f
	s_cselect_b64 vcc, -1, 0
	s_cmpk_lt_i32 s9, 0xff81
	s_cselect_b64 s[8:9], -1, 0
	v_cndmask_b32_e64 v64, 0, v157, s[8:9]
	v_cndmask_b32_e32 v64, v64, v158, vcc
	v_sub_f32_e32 v64, v64, v166
	v_mov_b32_e32 v65, v64
	v_mov_b32_e32 v66, v64
	v_mov_b32_e32 v67, v64
	v_mov_b32_e32 v68, v64
	v_mov_b32_e32 v69, v64
	v_mov_b32_e32 v70, v64
	v_mov_b32_e32 v71, v64
	v_mov_b32_e32 v72, v64
	v_mov_b32_e32 v73, v64
	v_mov_b32_e32 v74, v64
	v_mov_b32_e32 v75, v64
	v_mov_b32_e32 v76, v64
	v_mov_b32_e32 v77, v64
	v_mov_b32_e32 v78, v64
	v_mov_b32_e32 v79, v64
	s_addk_i32 s10, 0xffa1
	s_waitcnt lgkmcnt(3)
	v_mfma_f32_32x32x16_bf16 v[80:95], v[172:175], v[96:99], v[64:79]
	s_waitcnt lgkmcnt(2)
	v_mfma_f32_32x32x16_bf16 v[64:79], v[176:179], v[96:99], v[64:79]
	s_add_i32 s100, s42, 2
	s_cmp_ge_i32 s100, s33
	s_cbranch_scc1 .Ldqk1_nokld
	s_mov_b64 s[100:101], 0x4000
	global_load_dwordx4 v[116:119], v[152:153], off
	v_lshl_add_u64 v[112:113], v[152:153], 0, s[100:101]
	v_lshl_add_u64 v[136:137], v[112:113], 0, s[100:101]
	v_lshl_add_u64 v[140:141], v[136:137], 0, s[100:101]
	global_load_dwordx4 v[112:115], v[112:113], off
	global_load_dwordx4 v[136:139], v[136:137], off
	global_load_dwordx4 v[140:143], v[140:141], off

; #define MFMA(a, b, c) __builtin_amdgcn_mfma_f32_32x32x16_bf16((a), (b), (c), 0, 0, 0)
; DI int crow(int i, int h) { return (i & 3) + 8 * (i >> 2) + 4 * h; }
; DI void load_vtile(u32x4 (&rv)[4], const u16* __restrict__ vbase, int Lp, int key0, unsigned voffV) {
;   const char* ub = (const char*)vbase + (long)key0 * 2;
; #pragma unroll
;   for (int i = 0; i < 4; ++i) rv[i] = *(const u32x4*)(ub + (long)(32 * i) * Lp * 2 + voffV);
; }
; DI void mla_item(const Params& p, const GroupP& g, int item, char* smem, bool dry) {
;     ...
;       for (int ks = 0; ks < 12; ++ks) {
;         if (ks + 2 < 12) {
;           kf[(ks + 2) % 3][0] = *(const bf16x8*)(krd + (ks + 2) * 32);
;           kf[(ks + 2) % 3][1] = *(const bf16x8*)(krd + 32 * 400 + (ks + 2) * 32);
;           __builtin_amdgcn_sched_group_barrier(0x100, 2, 0);
;         }
;         sa[0] = MFMA(kf[ks % 3][0], qf[ks], sa[0]);
;         sa[1] = MFMA(kf[ks % 3][1], qf[ks], sa[1]);
;         __builtin_amdgcn_sched_group_barrier(0x008, 2, 0);
;       }
;     }
;     if (kt == nkt - 1) {
;       asm volatile("; masked tail tile" ::: "memory");
; #pragma unroll
;       for (int kb = 0; kb < 2; ++kb)
; #pragma unroll
;         for (int i = 0; i < 16; ++i)
;           if (kt * 64 + kb * 32 + crow(i, lh) >= L) sa[kb][i] = -1e30f;
;     }
;     __syncthreads();
;     if (more) { storeK(); load_vtile(rv, vbase, Lp, (kt + 1) * 64, voffV); }
.Lqk1_nokld:
	s_waitcnt lgkmcnt(5)
	v_mfma_f32_32x32x16_bf16 v[80:95], v[240:243], v[100:103], v[80:95]
	s_waitcnt lgkmcnt(4)
	v_mfma_f32_32x32x16_bf16 v[64:79], v[244:247], v[100:103], v[64:79]
	ds_read_b128 v[240:243], v184 offset:128
	ds_read_b128 v[244:247], v184 offset:12928
	s_waitcnt lgkmcnt(5)
	v_mfma_f32_32x32x16_bf16 v[80:95], v[248:251], v[104:107], v[80:95]
	s_waitcnt lgkmcnt(4)
	v_mfma_f32_32x32x16_bf16 v[64:79], v[206:209], v[104:107], v[64:79]
	ds_read_b128 v[206:209], v184 offset:160
	ds_read_b128 v[248:251], v184 offset:12960
	s_waitcnt lgkmcnt(5)
	v_mfma_f32_32x32x16_bf16 v[80:95], v[232:235], v[108:111], v[80:95]
	s_waitcnt lgkmcnt(4)
	v_mfma_f32_32x32x16_bf16 v[64:79], v[236:239], v[108:111], v[64:79]
	ds_read_b128 v[232:235], v184 offset:192
	ds_read_b128 v[236:239], v184 offset:12992
	ds_write2_b64 v227, v[152:153], v[154:155] offset0:128 offset1:130
	s_waitcnt lgkmcnt(6)
	v_mfma_f32_32x32x16_bf16 v[80:95], v[240:243], v[112:115], v[80:95]
	s_waitcnt lgkmcnt(5)
	v_mfma_f32_32x32x16_bf16 v[64:79], v[244:247], v[112:115], v[64:79]
	ds_read_b128 v[240:243], v184 offset:224
	ds_read_b128 v[244:247], v184 offset:13024
	ds_write2_b64 v228, v[156:157], v[158:159] offset0:192 offset1:194
	s_waitcnt lgkmcnt(7)
	v_mfma_f32_32x32x16_bf16 v[80:95], v[206:209], v[116:119], v[80:95]
	s_waitcnt lgkmcnt(6)
	v_mfma_f32_32x32x16_bf16 v[64:79], v[248:251], v[116:119], v[64:79]
	ds_read_b128 v[206:209], v184 offset:256
	ds_read_b128 v[248:251], v184 offset:13056
	ds_write2_b64 v229, v[164:165], v[166:167] offset1:2
	s_waitcnt lgkmcnt(8)
	v_mfma_f32_32x32x16_bf16 v[80:95], v[232:235], v[120:123], v[80:95]
	s_waitcnt lgkmcnt(7)
	v_mfma_f32_32x32x16_bf16 v[64:79], v[236:239], v[120:123], v[64:79]
	ds_read_b128 v[232:235], v184 offset:288
	ds_read_b128 v[236:239], v184 offset:13088
	ds_write2_b64 v230, v[168:169], v[170:171] offset0:64 offset1:66
	s_cmp_ge_i32 s92, s33
	s_cbranch_scc1 .Lpvm1_novl
	v_lshl_add_u64 v[152:153], v[194:195], 0, s[94:95]
	v_lshl_add_u64 v[156:157], v[152:153], 0, s[96:97]
	v_lshl_add_u64 v[164:165], v[156:157], 0, s[96:97]
	v_lshl_add_u64 v[168:169], v[164:165], 0, s[96:97]
	global_load_dwordx4 v[152:155], v[152:153], off
	global_load_dwordx4 v[156:159], v[156:157], off
	global_load_dwordx4 v[164:167], v[164:165], off
	global_load_dwordx4 v[168:171], v[168:169], off
.Lpvm1_novl:
	s_waitcnt lgkmcnt(8)
	v_mfma_f32_32x32x16_bf16 v[80:95], v[240:243], v[124:127], v[80:95]
	s_waitcnt lgkmcnt(7)
	v_mfma_f32_32x32x16_bf16 v[64:79], v[244:247], v[124:127], v[64:79]
	ds_read_b128 v[240:243], v184 offset:320
	ds_read_b128 v[244:247], v184 offset:13120
	s_waitcnt lgkmcnt(7)
	v_mfma_f32_32x32x16_bf16 v[80:95], v[206:209], v[128:131], v[80:95]
	s_waitcnt lgkmcnt(6)
	v_mfma_f32_32x32x16_bf16 v[64:79], v[248:251], v[128:131], v[64:79]
	ds_read_b128 v[206:209], v184 offset:352
	ds_read_b128 v[248:251], v184 offset:13152
	s_waitcnt lgkmcnt(6)
	v_mfma_f32_32x32x16_bf16 v[80:95], v[232:235], v[132:135], v[80:95]
	s_waitcnt lgkmcnt(5)
	v_mfma_f32_32x32x16_bf16 v[64:79], v[236:239], v[132:135], v[64:79]
	s_waitcnt lgkmcnt(3)
	v_mfma_f32_32x32x16_bf16 v[80:95], v[240:243], v[136:139], v[80:95]
	s_waitcnt lgkmcnt(2)
	v_mfma_f32_32x32x16_bf16 v[64:79], v[244:247], v[136:139], v[64:79]
	s_waitcnt lgkmcnt(1)
	v_mfma_f32_32x32x16_bf16 v[80:95], v[206:209], v[140:143], v[80:95]
	s_waitcnt lgkmcnt(0)
	v_mfma_f32_32x32x16_bf16 v[64:79], v[248:251], v[140:143], v[64:79]
	s_cmp_lg_u32 s33, s92
	s_cbranch_scc1 .LBB0_229
	s_nop 8
	v_cndmask_b32_e64 v95, v214, v95, s[8:9]
	v_cndmask_b32_e64 v94, v214, v94, s[12:13]
	v_cndmask_b32_e64 v93, v214, v93, s[14:15]
	v_cndmask_b32_e64 v92, v214, v92, s[16:17]
	v_cndmask_b32_e64 v91, v214, v91, s[18:19]
	v_cndmask_b32_e64 v90, v214, v90, s[20:21]
	v_cndmask_b32_e64 v89, v214, v89, s[22:23]
	v_cndmask_b32_e64 v88, v214, v88, s[24:25]
	v_cndmask_b32_e64 v87, v214, v87, s[26:27]
	v_cndmask_b32_e64 v86, v214, v86, s[28:29]
	v_cndmask_b32_e64 v85, v214, v85, s[30:31]
	v_cndmask_b32_e64 v84, v214, v84, s[34:35]
	v_cndmask_b32_e64 v83, v214, v83, s[36:37]
	v_cndmask_b32_e64 v82, v214, v82, s[38:39]
	v_cndmask_b32_e64 v81, v214, v81, s[40:41]
	v_cndmask_b32_e64 v80, v214, v80, s[42:43]
	v_cndmask_b32_e64 v79, v214, v79, s[10:11]
	v_cndmask_b32_e64 v78, v214, v78, s[44:45]
	v_cndmask_b32_e64 v77, v214, v77, s[46:47]
	v_cndmask_b32_e64 v76, v214, v76, s[48:49]
	v_cndmask_b32_e64 v75, v214, v75, s[50:51]
	v_cndmask_b32_e64 v74, v214, v74, s[52:53]
	v_cndmask_b32_e64 v73, v214, v73, s[54:55]
	v_cndmask_b32_e64 v72, v214, v72, s[56:57]
	v_cndmask_b32_e64 v71, v214, v71, s[58:59]
	v_cndmask_b32_e64 v70, v214, v70, s[60:61]
	v_cndmask_b32_e64 v69, v214, v69, s[62:63]
	v_cndmask_b32_e64 v68, v214, v68, s[64:65]
	v_cndmask_b32_e64 v67, v214, v67, s[66:67]
	v_cndmask_b32_e64 v66, v214, v66, s[68:69]
	v_cndmask_b32_e64 v65, v214, v65, s[70:71]
	v_cndmask_b32_e64 v64, v214, v64, s[72:73]
